# scan: in-place unpack of the prefetched u moved from the end of the step to the top of the next (under the first fragment reads)
# speedup vs baseline: 1.0073x; 1.0073x over previous
.LBB0_377:
	s_or_b64 exec, exec, s[76:77]
	s_waitcnt lgkmcnt(0)
	s_barrier
	s_ashr_i32 s79, s78, 31
	s_mov_b64 s[76:77], -1
	s_and_b64 vcc, exec, s[6:7]
	s_cbranch_vccz .LBB0_381
	s_waitcnt vmcnt(16)
	v_mov_b32_e32 v242, 0x3020706
	v_mov_b32_e32 v243, 0x5040100
	v_cndmask_b32_e64 v242, v242, v243, s[40:41]
	v_or_b32_e32 v0, s78, v210
	v_ashrrev_i32_e32 v1, 31, v0
	s_lshl_b64 s[28:29], s[78:79], 14
	v_lshl_add_u64 v[0:1], v[0:1], 2, s[8:9]
	v_lshl_add_u64 v[24:25], v[214:215], 0, s[28:29]
	global_load_dword v164, v[0:1], off
	global_load_dwordx4 v[0:3], v[24:25], off
	global_load_dwordx4 v[4:7], v[24:25], off offset:1024
	global_load_dwordx4 v[8:11], v[24:25], off offset:2048
	global_load_dwordx4 v[12:15], v[24:25], off offset:3072
	s_ashr_i32 s76, s26, 2
	s_lshl_b32 s4, s24, 1
	s_ashr_i32 s77, s76, 31
	s_and_b32 s4, s4, 0x300
	s_lshl_b64 s[76:77], s[76:77], 21
	s_or_b32 s4, s76, s4
	s_add_u32 s27, s17, s4
	v_mov_b32_e32 v32, 0
	s_addc_u32 s28, s20, s77
	s_mov_b32 s29, 0
	s_mov_b64 s[78:79], 0
	v_mov_b32_e32 v33, v32
	v_mov_b32_e32 v34, v32
	v_mov_b32_e32 v35, v32
	v_mov_b32_e32 v36, v32
	v_mov_b32_e32 v37, v32
	v_mov_b32_e32 v38, v32
	v_mov_b32_e32 v39, v32
	v_mov_b32_e32 v40, v32
	v_mov_b32_e32 v41, v32
	v_mov_b32_e32 v42, v32
	v_mov_b32_e32 v43, v32
	v_mov_b32_e32 v44, v32
	v_mov_b32_e32 v45, v32
	v_mov_b32_e32 v46, v32
	v_mov_b32_e32 v47, v32
	v_mov_b32_e32 v48, v32
	v_mov_b32_e32 v49, v32
	v_mov_b32_e32 v50, v32
	v_mov_b32_e32 v51, v32
	s_waitcnt vmcnt(5)
	v_mov_b32_e32 v52, v32
	v_mov_b32_e32 v53, v32
	v_mov_b32_e32 v54, v32
	v_mov_b32_e32 v55, v32
	v_mov_b32_e32 v56, v32
	v_mov_b32_e32 v57, v32
	v_mov_b32_e32 v58, v32
	v_mov_b32_e32 v59, v32
	v_mov_b32_e32 v60, v32
	v_mov_b32_e32 v61, v32
	v_mov_b32_e32 v62, v32
	v_mov_b32_e32 v63, v32
	v_mov_b32_e32 v64, v32
	v_mov_b32_e32 v65, v32
	v_mov_b32_e32 v66, v32
	v_mov_b32_e32 v67, v32
	v_mov_b32_e32 v68, v32
	v_mov_b32_e32 v69, v32
	v_mov_b32_e32 v70, v32
	v_mov_b32_e32 v71, v32
	v_mov_b32_e32 v72, v32
	v_mov_b32_e32 v73, v32
	v_mov_b32_e32 v74, v32
	v_mov_b32_e32 v75, v32
	v_mov_b32_e32 v76, v32
	v_mov_b32_e32 v77, v32
	v_mov_b32_e32 v78, v32
	v_mov_b32_e32 v79, v32
	v_mov_b32_e32 v80, v32
	v_mov_b32_e32 v81, v32
	v_mov_b32_e32 v82, v32
	v_mov_b32_e32 v83, v32
	v_mov_b32_e32 v84, v32
	v_mov_b32_e32 v85, v32
	v_mov_b32_e32 v86, v32
	v_mov_b32_e32 v87, v32
	v_mov_b32_e32 v88, v32
	v_mov_b32_e32 v89, v32
	v_mov_b32_e32 v90, v32
	v_mov_b32_e32 v91, v32
	v_mov_b32_e32 v92, v32
	v_mov_b32_e32 v93, v32
	v_mov_b32_e32 v94, v32
	v_mov_b32_e32 v95, v32
	s_waitcnt vmcnt(0)
.LBB0_379:
	s_bitcmp1_b32 s29, 0
	s_cselect_b32 s34, 0xf400, 0
	s_add_i32 s30, s22, s29
	s_ashr_i32 s31, s30, 31
	s_lshl_b64 s[30:31], s[30:31], 14
	v_lshl_add_u64 v[240:241], v[214:215], 0, s[30:31]
	v_add_u32_e32 v194, s34, v235
	v_readlane_b32 s4, v164, s29
	s_add_i32 s29, s29, 1
	v_add_u32_e32 v165, v194, v236
	v_add_u32_e32 v194, v194, v244
	v_add_u32_e32 v195, v194, v236
	ds_read_b128 v[96:99], v165
	ds_read_b128 v[166:169], v165 offset:32
	ds_read_b128 v[100:103], v165 offset:8704
	ds_read_b128 v[170:173], v165 offset:8736
	ds_read_b128 v[104:107], v165 offset:17408
	ds_read_b128 v[174:177], v165 offset:17440
	ds_read_b128 v[108:111], v165 offset:26112
	ds_read_b128 v[178:181], v165 offset:26144
	v_cvt_pk_bf16_f32 v182, v80, v81
	v_cvt_pk_bf16_f32 v183, v82, v83
	v_cvt_pk_bf16_f32 v184, v84, v85
	v_cvt_pk_bf16_f32 v185, v86, v87
	s_waitcnt vmcnt(16)
	v_and_b32_e32 v31, 0xffff0000, v15
	v_lshlrev_b32_e32 v30, 16, v15
	v_and_b32_e32 v29, 0xffff0000, v14
	v_lshlrev_b32_e32 v28, 16, v14
	v_and_b32_e32 v27, 0xffff0000, v13
	v_lshlrev_b32_e32 v26, 16, v13
	v_and_b32_e32 v25, 0xffff0000, v12
	v_lshlrev_b32_e32 v24, 16, v12
	v_and_b32_e32 v23, 0xffff0000, v11
	v_lshlrev_b32_e32 v22, 16, v11
	v_and_b32_e32 v21, 0xffff0000, v10
	v_lshlrev_b32_e32 v20, 16, v10
	v_and_b32_e32 v19, 0xffff0000, v9
	v_lshlrev_b32_e32 v18, 16, v9
	v_and_b32_e32 v17, 0xffff0000, v8
	v_lshlrev_b32_e32 v16, 16, v8
	v_and_b32_e32 v15, 0xffff0000, v7
	v_lshlrev_b32_e32 v14, 16, v7
	v_and_b32_e32 v13, 0xffff0000, v6
	v_lshlrev_b32_e32 v12, 16, v6
	v_and_b32_e32 v11, 0xffff0000, v5
	v_lshlrev_b32_e32 v10, 16, v5
	v_and_b32_e32 v9, 0xffff0000, v4
	v_lshlrev_b32_e32 v8, 16, v4
	v_and_b32_e32 v7, 0xffff0000, v3
	v_lshlrev_b32_e32 v6, 16, v3
	v_and_b32_e32 v5, 0xffff0000, v2
	v_lshlrev_b32_e32 v4, 16, v2
	v_and_b32_e32 v3, 0xffff0000, v1
	v_lshlrev_b32_e32 v2, 16, v1
	v_and_b32_e32 v1, 0xffff0000, v0
	v_lshlrev_b32_e32 v0, 16, v0
	s_waitcnt lgkmcnt(7)
	s_nop 0
	v_mfma_f32_32x32x16_bf16 v[128:143], v[96:99], v[182:185], v[0:15]
	s_waitcnt lgkmcnt(5)
	v_mfma_f32_32x32x16_bf16 v[144:159], v[100:103], v[182:185], v[16:31]
	s_waitcnt lgkmcnt(3)
	v_mfma_f32_32x32x16_bf16 v[112:127], v[104:107], v[182:185], 0
	s_waitcnt lgkmcnt(1)
	v_mfma_f32_32x32x16_bf16 v[96:111], v[108:111], v[182:185], 0
	global_load_dwordx4 v[0:3], v[240:241], off
	global_load_dwordx4 v[4:7], v[240:241], off offset:1024
	global_load_dwordx4 v[8:11], v[240:241], off offset:2048
	global_load_dwordx4 v[12:15], v[240:241], off offset:3072
	ds_read_b128 v[182:185], v165 offset:26176
	ds_read_b128 v[186:189], v165 offset:17472
	ds_read_b128 v[190:193], v165 offset:8768
	ds_read_b128 v[220:223], v165 offset:64
	v_cvt_pk_bf16_f32 v246, v88, v89
	v_cvt_pk_bf16_f32 v247, v90, v91
	v_cvt_pk_bf16_f32 v248, v92, v93
	v_cvt_pk_bf16_f32 v249, v94, v95
	s_nop 1
	v_mfma_f32_32x32x16_bf16 v[128:143], v[166:169], v[246:249], v[128:143]
	v_mfma_f32_32x32x16_bf16 v[144:159], v[170:173], v[246:249], v[144:159]
	v_mfma_f32_32x32x16_bf16 v[112:127], v[174:177], v[246:249], v[112:127]
	s_waitcnt lgkmcnt(4)
	v_mfma_f32_32x32x16_bf16 v[96:111], v[178:181], v[246:249], v[96:111]
	ds_read_b128 v[166:169], v165 offset:96
	ds_read_b128 v[170:173], v165 offset:8800
	ds_read_b128 v[174:177], v165 offset:17504
	ds_read_b128 v[178:181], v165 offset:26208
	v_cvt_pk_bf16_f32 v246, v64, v65
	v_cvt_pk_bf16_f32 v247, v66, v67
	v_cvt_pk_bf16_f32 v248, v68, v69
	v_cvt_pk_bf16_f32 v249, v70, v71
	s_waitcnt lgkmcnt(4)
	s_nop 0
	v_mfma_f32_32x32x16_bf16 v[128:143], v[220:223], v[246:249], v[128:143]
	v_mfma_f32_32x32x16_bf16 v[144:159], v[190:193], v[246:249], v[144:159]
	v_mfma_f32_32x32x16_bf16 v[112:127], v[186:189], v[246:249], v[112:127]
	v_mfma_f32_32x32x16_bf16 v[96:111], v[182:185], v[246:249], v[96:111]
	ds_read_b128 v[182:185], v165 offset:26240
	ds_read_b128 v[186:189], v165 offset:17536
	ds_read_b128 v[190:193], v165 offset:8832
	ds_read_b128 v[220:223], v165 offset:128
	v_cvt_pk_bf16_f32 v246, v72, v73
	v_cvt_pk_bf16_f32 v247, v74, v75
	v_cvt_pk_bf16_f32 v248, v76, v77
	v_cvt_pk_bf16_f32 v249, v78, v79
	s_waitcnt lgkmcnt(7)
	s_nop 0
	v_mfma_f32_32x32x16_bf16 v[128:143], v[166:169], v[246:249], v[128:143]
	s_waitcnt lgkmcnt(6)
	v_mfma_f32_32x32x16_bf16 v[144:159], v[170:173], v[246:249], v[144:159]
	s_waitcnt lgkmcnt(5)
	v_mfma_f32_32x32x16_bf16 v[112:127], v[174:177], v[246:249], v[112:127]
	s_waitcnt lgkmcnt(4)
	v_mfma_f32_32x32x16_bf16 v[96:111], v[178:181], v[246:249], v[96:111]
	ds_read_b128 v[166:169], v165 offset:160
	ds_read_b128 v[170:173], v165 offset:8864
	ds_read_b128 v[174:177], v165 offset:17568
	ds_read_b128 v[178:181], v165 offset:26272
	v_cvt_pk_bf16_f32 v246, v48, v49
	v_cvt_pk_bf16_f32 v247, v50, v51
	v_cvt_pk_bf16_f32 v248, v52, v53
	v_cvt_pk_bf16_f32 v249, v54, v55
	s_waitcnt lgkmcnt(4)
	s_nop 0
	v_mfma_f32_32x32x16_bf16 v[128:143], v[220:223], v[246:249], v[128:143]
	v_mfma_f32_32x32x16_bf16 v[144:159], v[190:193], v[246:249], v[144:159]
	v_mfma_f32_32x32x16_bf16 v[112:127], v[186:189], v[246:249], v[112:127]
	v_mfma_f32_32x32x16_bf16 v[96:111], v[182:185], v[246:249], v[96:111]
	ds_read_b128 v[182:185], v165 offset:26304
	ds_read_b128 v[186:189], v165 offset:17600
	ds_read_b128 v[190:193], v165 offset:8896
	ds_read_b128 v[220:223], v165 offset:192
	v_cvt_pk_bf16_f32 v246, v56, v57
	v_cvt_pk_bf16_f32 v247, v58, v59
	v_cvt_pk_bf16_f32 v248, v60, v61
	v_cvt_pk_bf16_f32 v249, v62, v63
	s_waitcnt lgkmcnt(7)
	s_nop 0
	v_mfma_f32_32x32x16_bf16 v[128:143], v[166:169], v[246:249], v[128:143]
	s_waitcnt lgkmcnt(6)
	v_mfma_f32_32x32x16_bf16 v[144:159], v[170:173], v[246:249], v[144:159]
	s_waitcnt lgkmcnt(5)
	v_mfma_f32_32x32x16_bf16 v[112:127], v[174:177], v[246:249], v[112:127]
	s_waitcnt lgkmcnt(4)
	v_mfma_f32_32x32x16_bf16 v[96:111], v[178:181], v[246:249], v[96:111]
	ds_read_b128 v[166:169], v165 offset:224
	ds_read_b128 v[170:173], v165 offset:8928
	ds_read_b128 v[174:177], v165 offset:17632
	ds_read_b128 v[178:181], v165 offset:26336
	v_cvt_pk_bf16_f32 v246, v32, v33
	v_cvt_pk_bf16_f32 v247, v34, v35
	v_cvt_pk_bf16_f32 v248, v36, v37
	v_cvt_pk_bf16_f32 v249, v38, v39
	s_waitcnt lgkmcnt(4)
	s_nop 0
	v_mfma_f32_32x32x16_bf16 v[128:143], v[220:223], v[246:249], v[128:143]
	v_mfma_f32_32x32x16_bf16 v[144:159], v[190:193], v[246:249], v[144:159]
	v_mfma_f32_32x32x16_bf16 v[112:127], v[186:189], v[246:249], v[112:127]
	v_mfma_f32_32x32x16_bf16 v[96:111], v[182:185], v[246:249], v[96:111]
	ds_read_b128 v[182:185], v195 offset:57952
	ds_read_b128 v[186:189], v195 offset:57920
	ds_read_b128 v[190:193], v195 offset:57888
	ds_read_b128 v[220:223], v195 offset:57856
	ds_read_b128 v[246:249], v195 offset:53248
	ds_read_b128 v[250:253], v195 offset:53280
	v_cvt_pk_bf16_f32 v204, v40, v41
	v_cvt_pk_bf16_f32 v205, v42, v43
	v_cvt_pk_bf16_f32 v206, v44, v45
	v_cvt_pk_bf16_f32 v207, v46, v47
	s_waitcnt lgkmcnt(9)
	s_nop 0
	v_mfma_f32_32x32x16_bf16 v[128:143], v[166:169], v[204:207], v[128:143]
	s_waitcnt lgkmcnt(8)
	v_mfma_f32_32x32x16_bf16 v[144:159], v[170:173], v[204:207], v[144:159]
	s_waitcnt lgkmcnt(7)
	v_mfma_f32_32x32x16_bf16 v[112:127], v[174:177], v[204:207], v[112:127]
	s_waitcnt lgkmcnt(6)
	v_mfma_f32_32x32x16_bf16 v[96:111], v[178:181], v[204:207], v[96:111]
	v_add_u32_e32 v165, v194, v196
	s_nop 4
	v_cvt_pk_bf16_f32 v128, v128, v129
	v_cvt_pk_bf16_f32 v129, v130, v131
	v_cvt_pk_bf16_f32 v130, v132, v133
	v_cvt_pk_bf16_f32 v131, v134, v135
	v_cvt_pk_bf16_f32 v132, v136, v137
	v_cvt_pk_bf16_f32 v133, v138, v139
	v_cvt_pk_bf16_f32 v134, v140, v141
	v_cvt_pk_bf16_f32 v135, v142, v143
	v_cvt_pk_bf16_f32 v136, v144, v145
	v_cvt_pk_bf16_f32 v137, v146, v147
	v_cvt_pk_bf16_f32 v138, v148, v149
	v_cvt_pk_bf16_f32 v139, v150, v151
	v_cvt_pk_bf16_f32 v140, v152, v153
	v_cvt_pk_bf16_f32 v141, v154, v155
	v_cvt_pk_bf16_f32 v142, v156, v157
	v_cvt_pk_bf16_f32 v143, v158, v159
	ds_read_b128 v[144:147], v165 offset:34816
	ds_read_b128 v[148:151], v165 offset:34848
	ds_read_b128 v[152:155], v165 offset:34880
	ds_read_b128 v[156:159], v165 offset:34912
	s_waitcnt lgkmcnt(6)
	v_mfma_f32_32x32x16_bf16 v[96:111], v[220:223], v[128:131], v[96:111]
	v_mfma_f32_32x32x16_bf16 v[96:111], v[190:193], v[132:135], v[96:111]
	s_waitcnt lgkmcnt(5)
	v_mfma_f32_32x32x16_bf16 v[112:127], v[246:249], v[128:131], v[112:127]
	v_mfma_f32_32x32x16_bf16 v[96:111], v[186:189], v[136:139], v[96:111]
	s_waitcnt lgkmcnt(4)
	v_mfma_f32_32x32x16_bf16 v[112:127], v[250:253], v[132:135], v[112:127]
	v_mfma_f32_32x32x16_bf16 v[96:111], v[182:185], v[140:143], v[96:111]
	ds_read_b128 v[166:169], v165 offset:39424
	ds_read_b128 v[170:173], v165 offset:39456
	ds_read_b128 v[174:177], v165 offset:39520
	ds_read_b128 v[178:181], v165 offset:39488
	v_mul_f32_e64 v94, v94, s4
	v_mul_f32_e64 v95, v95, s4
	v_pk_mul_f32 v[92:93], v[92:93], s[4:5] op_sel_hi:[1,0]
	v_pk_mul_f32 v[90:91], v[90:91], s[4:5] op_sel_hi:[1,0]
	v_pk_mul_f32 v[88:89], v[88:89], s[4:5] op_sel_hi:[1,0]
	v_pk_mul_f32 v[86:87], v[86:87], s[4:5] op_sel_hi:[1,0]
	v_pk_mul_f32 v[84:85], v[84:85], s[4:5] op_sel_hi:[1,0]
	v_pk_mul_f32 v[82:83], v[82:83], s[4:5] op_sel_hi:[1,0]
	v_pk_mul_f32 v[80:81], v[80:81], s[4:5] op_sel_hi:[1,0]
	s_waitcnt lgkmcnt(7)
	s_nop 0
	v_mfma_f32_32x32x16_bf16 v[80:95], v[144:147], v[128:131], v[80:95]
	s_add_u32 s80, s27, s78
	s_addc_u32 s81, s28, s79
	v_cvt_pk_bf16_f32 v182, v112, v113
	v_cvt_pk_bf16_f32 v183, v114, v115
	v_cvt_pk_bf16_f32 v184, v116, v117
	v_cvt_pk_bf16_f32 v185, v118, v119
	s_waitcnt lgkmcnt(6)
	v_mfma_f32_32x32x16_bf16 v[80:95], v[148:151], v[132:135], v[80:95]
	v_cvt_pk_bf16_f32 v186, v120, v121
	v_cvt_pk_bf16_f32 v187, v122, v123
	v_cvt_pk_bf16_f32 v188, v124, v125
	v_cvt_pk_bf16_f32 v189, v126, v127
	s_waitcnt lgkmcnt(5)
	v_mfma_f32_32x32x16_bf16 v[80:95], v[152:155], v[136:139], v[80:95]
	v_mov_b32_dpp v190, v182 quad_perm:[1,0,3,2] row_mask:0xf bank_mask:0xf
	v_mov_b32_dpp v191, v183 quad_perm:[1,0,3,2] row_mask:0xf bank_mask:0xf
	v_mov_b32_dpp v192, v184 quad_perm:[1,0,3,2] row_mask:0xf bank_mask:0xf
	v_mov_b32_dpp v193, v185 quad_perm:[1,0,3,2] row_mask:0xf bank_mask:0xf
	v_add_u32_e32 v246, 0x2000, v213
	s_waitcnt lgkmcnt(4)
	v_mfma_f32_32x32x16_bf16 v[80:95], v[156:159], v[140:143], v[80:95]
	v_mov_b32_dpp v220, v186 quad_perm:[1,0,3,2] row_mask:0xf bank_mask:0xf
	v_mov_b32_dpp v221, v187 quad_perm:[1,0,3,2] row_mask:0xf bank_mask:0xf
	v_mov_b32_dpp v222, v188 quad_perm:[1,0,3,2] row_mask:0xf bank_mask:0xf
	v_mov_b32_dpp v223, v189 quad_perm:[1,0,3,2] row_mask:0xf bank_mask:0xf
	v_add_u32_e32 v247, 0x4000, v213
	ds_read_b128 v[144:147], v165 offset:44096
	ds_read_b128 v[148:151], v165 offset:44128
	ds_read_b128 v[152:155], v165 offset:44032
	ds_read_b128 v[156:159], v165 offset:44064
	v_mul_f32_e64 v78, v78, s4
	v_mul_f32_e64 v79, v79, s4
	v_pk_mul_f32 v[76:77], v[76:77], s[4:5] op_sel_hi:[1,0]
	v_pk_mul_f32 v[74:75], v[74:75], s[4:5] op_sel_hi:[1,0]
	v_pk_mul_f32 v[72:73], v[72:73], s[4:5] op_sel_hi:[1,0]
	v_pk_mul_f32 v[70:71], v[70:71], s[4:5] op_sel_hi:[1,0]
	v_pk_mul_f32 v[68:69], v[68:69], s[4:5] op_sel_hi:[1,0]
	v_pk_mul_f32 v[66:67], v[66:67], s[4:5] op_sel_hi:[1,0]
	v_pk_mul_f32 v[64:65], v[64:65], s[4:5] op_sel_hi:[1,0]
	s_waitcnt lgkmcnt(6)
	s_nop 0
	v_mfma_f32_32x32x16_bf16 v[64:79], v[170:173], v[128:131], v[64:79]
	v_perm_b32 v182, v190, v182, v242
	v_perm_b32 v183, v191, v183, v242
	v_perm_b32 v184, v192, v184, v242
	v_perm_b32 v185, v193, v185, v242
	v_add_u32_e32 v248, 0x6000, v213
	v_mfma_f32_32x32x16_bf16 v[64:79], v[166:169], v[132:135], v[64:79]
	v_perm_b32 v186, v220, v186, v242
	v_perm_b32 v187, v221, v187, v242
	v_perm_b32 v188, v222, v188, v242
	v_perm_b32 v189, v223, v189, v242
	s_waitcnt lgkmcnt(5)
	v_mfma_f32_32x32x16_bf16 v[64:79], v[174:177], v[136:139], v[64:79]
	global_store_dword v213, v182, s[80:81]
	global_store_dword v213, v183, s[80:81] offset:2048
	global_store_dword v246, v184, s[80:81]
	global_store_dword v246, v185, s[80:81] offset:2048
	s_waitcnt lgkmcnt(4)
	v_mfma_f32_32x32x16_bf16 v[64:79], v[178:181], v[140:143], v[64:79]
	global_store_dword v247, v186, s[80:81]
	global_store_dword v247, v187, s[80:81] offset:2048
	global_store_dword v248, v188, s[80:81]
	global_store_dword v248, v189, s[80:81] offset:2048
	ds_read_b128 v[166:169], v165 offset:48736
	ds_read_b128 v[170:173], v165 offset:48704
	ds_read_b128 v[174:177], v165 offset:48640
	ds_read_b128 v[178:181], v165 offset:48672
	v_mul_f32_e64 v62, v62, s4
	v_mul_f32_e64 v63, v63, s4
	v_pk_mul_f32 v[60:61], v[60:61], s[4:5] op_sel_hi:[1,0]
	v_pk_mul_f32 v[58:59], v[58:59], s[4:5] op_sel_hi:[1,0]
	v_pk_mul_f32 v[56:57], v[56:57], s[4:5] op_sel_hi:[1,0]
	v_pk_mul_f32 v[54:55], v[54:55], s[4:5] op_sel_hi:[1,0]
	v_pk_mul_f32 v[52:53], v[52:53], s[4:5] op_sel_hi:[1,0]
	v_pk_mul_f32 v[50:51], v[50:51], s[4:5] op_sel_hi:[1,0]
	v_pk_mul_f32 v[48:49], v[48:49], s[4:5] op_sel_hi:[1,0]
	s_waitcnt lgkmcnt(7)
	s_nop 0
	v_mfma_f32_32x32x16_bf16 v[48:63], v[144:147], v[128:131], v[48:63]
	v_cvt_pk_bf16_f32 v182, v96, v97
	v_cvt_pk_bf16_f32 v183, v98, v99
	v_cvt_pk_bf16_f32 v184, v100, v101
	v_cvt_pk_bf16_f32 v185, v102, v103
	s_waitcnt lgkmcnt(6)
	v_mfma_f32_32x32x16_bf16 v[48:63], v[148:151], v[132:135], v[48:63]
	v_cvt_pk_bf16_f32 v186, v104, v105
	v_cvt_pk_bf16_f32 v187, v106, v107
	v_cvt_pk_bf16_f32 v188, v108, v109
	v_cvt_pk_bf16_f32 v189, v110, v111
	s_waitcnt lgkmcnt(5)
	v_mfma_f32_32x32x16_bf16 v[48:63], v[152:155], v[136:139], v[48:63]
	v_mov_b32_dpp v190, v182 quad_perm:[1,0,3,2] row_mask:0xf bank_mask:0xf
	v_mov_b32_dpp v191, v183 quad_perm:[1,0,3,2] row_mask:0xf bank_mask:0xf
	v_mov_b32_dpp v192, v184 quad_perm:[1,0,3,2] row_mask:0xf bank_mask:0xf
	v_mov_b32_dpp v193, v185 quad_perm:[1,0,3,2] row_mask:0xf bank_mask:0xf
	v_add_u32_e32 v246, 0x8000, v213
	s_waitcnt lgkmcnt(4)
	v_mfma_f32_32x32x16_bf16 v[48:63], v[156:159], v[140:143], v[48:63]
	v_mov_b32_dpp v220, v186 quad_perm:[1,0,3,2] row_mask:0xf bank_mask:0xf
	v_mov_b32_dpp v221, v187 quad_perm:[1,0,3,2] row_mask:0xf bank_mask:0xf
	v_mov_b32_dpp v222, v188 quad_perm:[1,0,3,2] row_mask:0xf bank_mask:0xf
	v_mov_b32_dpp v223, v189 quad_perm:[1,0,3,2] row_mask:0xf bank_mask:0xf
	v_add_u32_e32 v247, 0xa000, v213
	v_pk_mul_f32 v[46:47], v[46:47], s[4:5] op_sel_hi:[1,0]
	v_pk_mul_f32 v[44:45], v[44:45], s[4:5] op_sel_hi:[1,0]
	v_pk_mul_f32 v[42:43], v[42:43], s[4:5] op_sel_hi:[1,0]
	v_pk_mul_f32 v[40:41], v[40:41], s[4:5] op_sel_hi:[1,0]
	v_pk_mul_f32 v[38:39], v[38:39], s[4:5] op_sel_hi:[1,0]
	v_pk_mul_f32 v[36:37], v[36:37], s[4:5] op_sel_hi:[1,0]
	v_pk_mul_f32 v[34:35], v[34:35], s[4:5] op_sel_hi:[1,0]
	v_pk_mul_f32 v[32:33], v[32:33], s[4:5] op_sel_hi:[1,0]
	s_waitcnt lgkmcnt(3)
	s_nop 0
	v_mfma_f32_32x32x16_bf16 v[32:47], v[166:169], v[128:131], v[32:47]
	v_perm_b32 v182, v190, v182, v242
	v_perm_b32 v183, v191, v183, v242
	v_perm_b32 v184, v192, v184, v242
	v_perm_b32 v185, v193, v185, v242
	v_add_u32_e32 v248, 0xc000, v213
	s_waitcnt lgkmcnt(2)
	v_mfma_f32_32x32x16_bf16 v[32:47], v[170:173], v[132:135], v[32:47]
	v_perm_b32 v186, v220, v186, v242
	v_perm_b32 v187, v221, v187, v242
	v_perm_b32 v188, v222, v188, v242
	v_perm_b32 v189, v223, v189, v242
	v_add_u32_e32 v249, 0xe000, v213
	s_waitcnt lgkmcnt(0)
	v_mfma_f32_32x32x16_bf16 v[32:47], v[178:181], v[136:139], v[32:47]
	global_store_dword v246, v182, s[80:81]
	global_store_dword v246, v183, s[80:81] offset:2048
	global_store_dword v247, v184, s[80:81]
	global_store_dword v247, v185, s[80:81] offset:2048
	v_mfma_f32_32x32x16_bf16 v[32:47], v[174:177], v[140:143], v[32:47]
	global_store_dword v248, v186, s[80:81]
	global_store_dword v248, v187, s[80:81] offset:2048
	global_store_dword v249, v188, s[80:81]
	global_store_dword v249, v189, s[80:81] offset:2048
	s_waitcnt lgkmcnt(0)
	s_barrier
	s_add_u32 s78, s78, 0x10000
	s_addc_u32 s79, s79, 0
	s_cmp_eq_u32 s78, 0x1f0000
	s_cbranch_scc0 .LBB0_379
	s_add_u32 s4, s17, s76
	s_addc_u32 s27, s20, s77
	s_lshl_b32 s28, s26, 8
	s_and_b32 s28, s28, 0x300
	s_add_u32 s4, s4, s28
	s_addc_u32 s27, s27, 0
	ds_read_b128 v[96:99], v237 offset:62464
	ds_read_b128 v[128:131], v237 offset:62496
	ds_read_b128 v[100:103], v238 offset:8704
	ds_read_b128 v[132:135], v238 offset:8736
	ds_read_b128 v[104:107], v238 offset:17408
	ds_read_b128 v[136:139], v238 offset:17440
	ds_read_b128 v[108:111], v238 offset:26112
	ds_read_b128 v[140:143], v238 offset:26144
	v_cvt_pk_bf16_f32 v80, v80, v81
	v_cvt_pk_bf16_f32 v81, v82, v83
	v_cvt_pk_bf16_f32 v82, v84, v85
	v_cvt_pk_bf16_f32 v83, v86, v87
	s_waitcnt vmcnt(16)
	v_and_b32_e32 v31, 0xffff0000, v15
	v_lshlrev_b32_e32 v30, 16, v15
	v_and_b32_e32 v29, 0xffff0000, v14
	v_lshlrev_b32_e32 v28, 16, v14
	v_and_b32_e32 v27, 0xffff0000, v13
	v_lshlrev_b32_e32 v26, 16, v13
	v_and_b32_e32 v25, 0xffff0000, v12
	v_lshlrev_b32_e32 v24, 16, v12
	v_and_b32_e32 v23, 0xffff0000, v11
	v_lshlrev_b32_e32 v22, 16, v11
	v_and_b32_e32 v21, 0xffff0000, v10
	v_lshlrev_b32_e32 v20, 16, v10
	v_and_b32_e32 v19, 0xffff0000, v9
	v_lshlrev_b32_e32 v18, 16, v9
	v_and_b32_e32 v17, 0xffff0000, v8
	v_lshlrev_b32_e32 v16, 16, v8
	v_and_b32_e32 v15, 0xffff0000, v7
	v_lshlrev_b32_e32 v14, 16, v7
	v_and_b32_e32 v13, 0xffff0000, v6
	v_lshlrev_b32_e32 v12, 16, v6
	v_and_b32_e32 v11, 0xffff0000, v5
	v_lshlrev_b32_e32 v10, 16, v5
	v_and_b32_e32 v9, 0xffff0000, v4
	v_lshlrev_b32_e32 v8, 16, v4
	v_and_b32_e32 v7, 0xffff0000, v3
	v_lshlrev_b32_e32 v6, 16, v3
	v_and_b32_e32 v5, 0xffff0000, v2
	v_lshlrev_b32_e32 v4, 16, v2
	v_and_b32_e32 v3, 0xffff0000, v1
	v_lshlrev_b32_e32 v2, 16, v1
	v_and_b32_e32 v1, 0xffff0000, v0
	v_lshlrev_b32_e32 v0, 16, v0
	s_waitcnt lgkmcnt(7)
	s_nop 0
	v_mfma_f32_32x32x16_bf16 v[0:15], v[96:99], v[80:83], v[0:15]
	s_waitcnt lgkmcnt(5)
	v_mfma_f32_32x32x16_bf16 v[16:31], v[100:103], v[80:83], v[16:31]
	s_waitcnt lgkmcnt(3)
	v_mfma_f32_32x32x16_bf16 v[112:127], v[104:107], v[80:83], 0
	s_waitcnt lgkmcnt(1)
	v_mfma_f32_32x32x16_bf16 v[96:111], v[108:111], v[80:83], 0
	ds_read_b128 v[80:83], v238 offset:26176
	ds_read_b128 v[84:87], v238 offset:17472
	ds_read_b128 v[144:147], v238 offset:8768
	ds_read_b128 v[148:151], v237 offset:62528
	v_cvt_pk_bf16_f32 v88, v88, v89
	v_cvt_pk_bf16_f32 v89, v90, v91
	v_cvt_pk_bf16_f32 v90, v92, v93
	v_cvt_pk_bf16_f32 v91, v94, v95
	s_nop 1
	v_mfma_f32_32x32x16_bf16 v[0:15], v[128:131], v[88:91], v[0:15]
	v_mfma_f32_32x32x16_bf16 v[16:31], v[132:135], v[88:91], v[16:31]
	v_mfma_f32_32x32x16_bf16 v[112:127], v[136:139], v[88:91], v[112:127]
	s_waitcnt lgkmcnt(4)
	v_mfma_f32_32x32x16_bf16 v[96:111], v[140:143], v[88:91], v[96:111]
	ds_read_b128 v[88:91], v237 offset:62560
	ds_read_b128 v[92:95], v238 offset:8800
	ds_read_b128 v[128:131], v238 offset:17504
	ds_read_b128 v[132:135], v238 offset:26208
	v_cvt_pk_bf16_f32 v64, v64, v65
	v_cvt_pk_bf16_f32 v65, v66, v67
	v_cvt_pk_bf16_f32 v66, v68, v69
	v_cvt_pk_bf16_f32 v67, v70, v71
	s_waitcnt lgkmcnt(4)
	s_nop 0
	v_mfma_f32_32x32x16_bf16 v[0:15], v[148:151], v[64:67], v[0:15]
	v_mfma_f32_32x32x16_bf16 v[16:31], v[144:147], v[64:67], v[16:31]
	v_mfma_f32_32x32x16_bf16 v[112:127], v[84:87], v[64:67], v[112:127]
	v_mfma_f32_32x32x16_bf16 v[96:111], v[80:83], v[64:67], v[96:111]
	ds_read_b128 v[64:67], v238 offset:26240
	ds_read_b128 v[68:71], v238 offset:17536
	ds_read_b128 v[80:83], v238 offset:8832
	ds_read_b128 v[84:87], v237 offset:62592
	v_cvt_pk_bf16_f32 v72, v72, v73
	v_cvt_pk_bf16_f32 v73, v74, v75
	v_cvt_pk_bf16_f32 v74, v76, v77
	v_cvt_pk_bf16_f32 v75, v78, v79
	s_waitcnt lgkmcnt(7)
	s_nop 0
	v_mfma_f32_32x32x16_bf16 v[0:15], v[88:91], v[72:75], v[0:15]
	s_waitcnt lgkmcnt(6)
	v_mfma_f32_32x32x16_bf16 v[16:31], v[92:95], v[72:75], v[16:31]
	s_waitcnt lgkmcnt(5)
	v_mfma_f32_32x32x16_bf16 v[112:127], v[128:131], v[72:75], v[112:127]
	s_waitcnt lgkmcnt(4)
	v_mfma_f32_32x32x16_bf16 v[96:111], v[132:135], v[72:75], v[96:111]
	ds_read_b128 v[72:75], v237 offset:62624
	ds_read_b128 v[76:79], v238 offset:8864
	ds_read_b128 v[88:91], v238 offset:17568
	ds_read_b128 v[92:95], v238 offset:26272
	v_cvt_pk_bf16_f32 v48, v48, v49
	v_cvt_pk_bf16_f32 v49, v50, v51
	v_cvt_pk_bf16_f32 v50, v52, v53
	v_cvt_pk_bf16_f32 v51, v54, v55
	s_waitcnt lgkmcnt(4)
	s_nop 0
	v_mfma_f32_32x32x16_bf16 v[0:15], v[84:87], v[48:51], v[0:15]
	v_mfma_f32_32x32x16_bf16 v[16:31], v[80:83], v[48:51], v[16:31]
	v_mfma_f32_32x32x16_bf16 v[112:127], v[68:71], v[48:51], v[112:127]
	v_mfma_f32_32x32x16_bf16 v[96:111], v[64:67], v[48:51], v[96:111]
	ds_read_b128 v[48:51], v238 offset:26304
	ds_read_b128 v[52:55], v238 offset:17600
	ds_read_b128 v[64:67], v238 offset:8896
	ds_read_b128 v[68:71], v237 offset:62656
	v_cvt_pk_bf16_f32 v56, v56, v57
	v_cvt_pk_bf16_f32 v57, v58, v59
	v_cvt_pk_bf16_f32 v58, v60, v61
	v_cvt_pk_bf16_f32 v59, v62, v63
	s_waitcnt lgkmcnt(7)
	s_nop 0
	v_mfma_f32_32x32x16_bf16 v[0:15], v[72:75], v[56:59], v[0:15]
	s_waitcnt lgkmcnt(6)
	v_mfma_f32_32x32x16_bf16 v[16:31], v[76:79], v[56:59], v[16:31]
	s_waitcnt lgkmcnt(5)
	v_mfma_f32_32x32x16_bf16 v[112:127], v[88:91], v[56:59], v[112:127]
	s_waitcnt lgkmcnt(4)
	v_mfma_f32_32x32x16_bf16 v[96:111], v[92:95], v[56:59], v[96:111]
	ds_read_b128 v[56:59], v237 offset:62688
	ds_read_b128 v[60:63], v238 offset:8928
	ds_read_b128 v[72:75], v238 offset:17632
	ds_read_b128 v[76:79], v238 offset:26336
	v_cvt_pk_bf16_f32 v32, v32, v33
	v_cvt_pk_bf16_f32 v33, v34, v35
	v_cvt_pk_bf16_f32 v34, v36, v37
	v_cvt_pk_bf16_f32 v35, v38, v39
	s_waitcnt lgkmcnt(4)
	s_nop 0
	v_mfma_f32_32x32x16_bf16 v[0:15], v[68:71], v[32:35], v[0:15]
	v_mfma_f32_32x32x16_bf16 v[16:31], v[64:67], v[32:35], v[16:31]
	v_mfma_f32_32x32x16_bf16 v[112:127], v[52:55], v[32:35], v[112:127]
	v_mfma_f32_32x32x16_bf16 v[96:111], v[48:51], v[32:35], v[96:111]
	ds_read_b128 v[32:35], v239 offset:4704
	ds_read_b128 v[36:39], v239 offset:4672
	ds_read_b128 v[48:51], v239 offset:4640
	ds_read_b128 v[52:55], v239 offset:4608
	ds_read_b128 v[64:67], v239
	ds_read_b128 v[68:71], v239 offset:32
	v_cvt_pk_bf16_f32 v40, v40, v41
	v_cvt_pk_bf16_f32 v41, v42, v43
	v_cvt_pk_bf16_f32 v42, v44, v45
	v_cvt_pk_bf16_f32 v43, v46, v47
	s_waitcnt lgkmcnt(9)
	s_nop 0
	v_mfma_f32_32x32x16_bf16 v[0:15], v[56:59], v[40:43], v[0:15]
	s_waitcnt lgkmcnt(8)
	v_mfma_f32_32x32x16_bf16 v[16:31], v[60:63], v[40:43], v[16:31]
	s_waitcnt lgkmcnt(7)
	v_mfma_f32_32x32x16_bf16 v[112:127], v[72:75], v[40:43], v[112:127]
	s_waitcnt lgkmcnt(6)
	v_mfma_f32_32x32x16_bf16 v[96:111], v[76:79], v[40:43], v[96:111]
	s_nop 5
	v_cvt_pk_bf16_f32 v0, v0, v1
	v_cvt_pk_bf16_f32 v1, v2, v3
	v_cvt_pk_bf16_f32 v2, v4, v5
	v_cvt_pk_bf16_f32 v3, v6, v7
	v_cvt_pk_bf16_f32 v4, v8, v9
	v_cvt_pk_bf16_f32 v5, v10, v11
	v_cvt_pk_bf16_f32 v6, v12, v13
	v_cvt_pk_bf16_f32 v7, v14, v15
	v_cvt_pk_bf16_f32 v8, v16, v17
	v_cvt_pk_bf16_f32 v9, v18, v19
	v_cvt_pk_bf16_f32 v10, v20, v21
	v_cvt_pk_bf16_f32 v11, v22, v23
	v_cvt_pk_bf16_f32 v12, v24, v25
	v_cvt_pk_bf16_f32 v13, v26, v27
	v_cvt_pk_bf16_f32 v14, v28, v29
	v_cvt_pk_bf16_f32 v15, v30, v31
	s_waitcnt lgkmcnt(2)
	v_mfma_f32_32x32x16_bf16 v[96:111], v[52:55], v[0:3], v[96:111]
	v_mfma_f32_32x32x16_bf16 v[96:111], v[48:51], v[4:7], v[96:111]
	s_waitcnt lgkmcnt(1)
	v_mfma_f32_32x32x16_bf16 v[112:127], v[64:67], v[0:3], v[112:127]
	v_mfma_f32_32x32x16_bf16 v[96:111], v[36:39], v[8:11], v[96:111]
	s_waitcnt lgkmcnt(0)
	v_mfma_f32_32x32x16_bf16 v[112:127], v[68:71], v[4:7], v[112:127]
	v_mfma_f32_32x32x16_bf16 v[96:111], v[32:35], v[12:15], v[96:111]
	v_mov_b32_e32 v1, v197
	v_mov_b32_e32 v2, v197
	s_add_u32 s76, s4, 0x1f0000
	s_nop 7
	v_mov_b32_dpp v1, v112 quad_perm:[1,0,3,2] row_mask:0xf bank_mask:0xf
	v_mov_b32_e32 v0, v213
	v_mov_b32_dpp v2, v113 quad_perm:[1,0,3,2] row_mask:0xf bank_mask:0xf
	v_cndmask_b32_e64 v1, v113, v1, s[40:41]
	s_addc_u32 s77, s27, 0
	v_cndmask_b32_e64 v2, v2, v112, s[40:41]
	v_cvt_pk_bf16_f32 v1, v2, v1
	global_store_dword v0, v1, s[76:77]
	v_mov_b32_e32 v1, v197
	v_mov_b32_e32 v2, v197
	s_nop 0
	v_mov_b32_dpp v1, v114 quad_perm:[1,0,3,2] row_mask:0xf bank_mask:0xf
	v_mov_b32_dpp v2, v115 quad_perm:[1,0,3,2] row_mask:0xf bank_mask:0xf
	v_cndmask_b32_e64 v2, v2, v114, s[40:41]
	v_cndmask_b32_e64 v1, v115, v1, s[40:41]
	v_cvt_pk_bf16_f32 v1, v2, v1
	v_add_u32_e32 v2, 0x800, v0
	global_store_dword v2, v1, s[76:77]
	v_mov_b32_e32 v1, v197
	v_mov_b32_e32 v2, v197
	s_nop 0
	v_mov_b32_dpp v1, v116 quad_perm:[1,0,3,2] row_mask:0xf bank_mask:0xf
	v_mov_b32_dpp v2, v117 quad_perm:[1,0,3,2] row_mask:0xf bank_mask:0xf
	v_cndmask_b32_e64 v2, v2, v116, s[40:41]
	v_cndmask_b32_e64 v1, v117, v1, s[40:41]
	v_cvt_pk_bf16_f32 v1, v2, v1
	v_add_u32_e32 v2, 0x2000, v0
	global_store_dword v2, v1, s[76:77]
	v_mov_b32_e32 v1, v197
	v_mov_b32_e32 v2, v197
	s_nop 0
	v_mov_b32_dpp v1, v118 quad_perm:[1,0,3,2] row_mask:0xf bank_mask:0xf
	v_mov_b32_dpp v2, v119 quad_perm:[1,0,3,2] row_mask:0xf bank_mask:0xf
	v_cndmask_b32_e64 v2, v2, v118, s[40:41]
	v_cndmask_b32_e64 v1, v119, v1, s[40:41]
	v_cvt_pk_bf16_f32 v1, v2, v1
	v_add_u32_e32 v2, 0x2800, v0
	global_store_dword v2, v1, s[76:77]
	v_mov_b32_e32 v1, v197
	v_mov_b32_e32 v2, v197
	s_nop 0
	v_mov_b32_dpp v1, v120 quad_perm:[1,0,3,2] row_mask:0xf bank_mask:0xf
	v_mov_b32_dpp v2, v121 quad_perm:[1,0,3,2] row_mask:0xf bank_mask:0xf
	v_cndmask_b32_e64 v2, v2, v120, s[40:41]
	v_cndmask_b32_e64 v1, v121, v1, s[40:41]
	v_cvt_pk_bf16_f32 v1, v2, v1
	v_add_u32_e32 v2, 0x4000, v0
	global_store_dword v2, v1, s[76:77]
	v_mov_b32_e32 v1, v197
	v_mov_b32_e32 v2, v197
	s_nop 0
	v_mov_b32_dpp v1, v122 quad_perm:[1,0,3,2] row_mask:0xf bank_mask:0xf
	v_mov_b32_dpp v2, v123 quad_perm:[1,0,3,2] row_mask:0xf bank_mask:0xf
	v_cndmask_b32_e64 v2, v2, v122, s[40:41]
	v_cndmask_b32_e64 v1, v123, v1, s[40:41]
	v_cvt_pk_bf16_f32 v1, v2, v1
	v_add_u32_e32 v2, 0x4800, v0
	global_store_dword v2, v1, s[76:77]
	v_mov_b32_e32 v1, v197
	v_mov_b32_e32 v2, v197
	s_nop 0
	v_mov_b32_dpp v1, v124 quad_perm:[1,0,3,2] row_mask:0xf bank_mask:0xf
	v_mov_b32_dpp v2, v125 quad_perm:[1,0,3,2] row_mask:0xf bank_mask:0xf
	v_cndmask_b32_e64 v2, v2, v124, s[40:41]
	v_cndmask_b32_e64 v1, v125, v1, s[40:41]
	v_cvt_pk_bf16_f32 v1, v2, v1
	v_add_u32_e32 v2, 0x6000, v0
	global_store_dword v2, v1, s[76:77]
	v_mov_b32_e32 v1, v197
	v_mov_b32_e32 v2, v197
	s_nop 0
	v_mov_b32_dpp v1, v126 quad_perm:[1,0,3,2] row_mask:0xf bank_mask:0xf
	v_mov_b32_dpp v2, v127 quad_perm:[1,0,3,2] row_mask:0xf bank_mask:0xf
	v_cndmask_b32_e64 v2, v2, v126, s[40:41]
	v_cndmask_b32_e64 v1, v127, v1, s[40:41]
	v_cvt_pk_bf16_f32 v1, v2, v1
	v_add_u32_e32 v2, 0x6800, v0
	global_store_dword v2, v1, s[76:77]
	v_mov_b32_e32 v1, v197
	v_mov_b32_e32 v2, v197
	s_nop 0
	v_mov_b32_dpp v1, v96 quad_perm:[1,0,3,2] row_mask:0xf bank_mask:0xf
	v_mov_b32_dpp v2, v97 quad_perm:[1,0,3,2] row_mask:0xf bank_mask:0xf
	v_cndmask_b32_e64 v2, v2, v96, s[40:41]
	v_cndmask_b32_e64 v1, v97, v1, s[40:41]
	v_cvt_pk_bf16_f32 v1, v2, v1
	v_add_u32_e32 v2, 0x8000, v0
	global_store_dword v2, v1, s[76:77]
	v_mov_b32_e32 v1, v197
	v_mov_b32_e32 v2, v197
	s_nop 0
	v_mov_b32_dpp v1, v98 quad_perm:[1,0,3,2] row_mask:0xf bank_mask:0xf
	v_mov_b32_dpp v2, v99 quad_perm:[1,0,3,2] row_mask:0xf bank_mask:0xf
	v_cndmask_b32_e64 v2, v2, v98, s[40:41]
	v_cndmask_b32_e64 v1, v99, v1, s[40:41]
	v_cvt_pk_bf16_f32 v1, v2, v1
	v_add_u32_e32 v2, 0x8800, v0
	global_store_dword v2, v1, s[76:77]
	v_mov_b32_e32 v1, v197
	v_mov_b32_e32 v2, v197
	s_nop 0
	v_mov_b32_dpp v1, v100 quad_perm:[1,0,3,2] row_mask:0xf bank_mask:0xf
	v_mov_b32_dpp v2, v101 quad_perm:[1,0,3,2] row_mask:0xf bank_mask:0xf
	v_cndmask_b32_e64 v2, v2, v100, s[40:41]
	v_cndmask_b32_e64 v1, v101, v1, s[40:41]
	v_cvt_pk_bf16_f32 v1, v2, v1
	v_add_u32_e32 v2, 0xa000, v0
	global_store_dword v2, v1, s[76:77]
	v_mov_b32_e32 v1, v197
	v_mov_b32_e32 v2, v197
	s_nop 0
	v_mov_b32_dpp v1, v102 quad_perm:[1,0,3,2] row_mask:0xf bank_mask:0xf
	v_mov_b32_dpp v2, v103 quad_perm:[1,0,3,2] row_mask:0xf bank_mask:0xf
	v_cndmask_b32_e64 v2, v2, v102, s[40:41]
	v_cndmask_b32_e64 v1, v103, v1, s[40:41]
	v_cvt_pk_bf16_f32 v1, v2, v1
	v_add_u32_e32 v2, 0xa800, v0
	global_store_dword v2, v1, s[76:77]
	v_mov_b32_e32 v1, v197
	v_mov_b32_e32 v2, v197
	s_nop 0
	v_mov_b32_dpp v1, v104 quad_perm:[1,0,3,2] row_mask:0xf bank_mask:0xf
	v_mov_b32_dpp v2, v105 quad_perm:[1,0,3,2] row_mask:0xf bank_mask:0xf
	v_cndmask_b32_e64 v2, v2, v104, s[40:41]
	v_cndmask_b32_e64 v1, v105, v1, s[40:41]
	v_cvt_pk_bf16_f32 v1, v2, v1
	v_add_u32_e32 v2, 0xc000, v0
	global_store_dword v2, v1, s[76:77]
	v_mov_b32_e32 v1, v197
	v_mov_b32_e32 v2, v197
	s_nop 0
	v_mov_b32_dpp v1, v106 quad_perm:[1,0,3,2] row_mask:0xf bank_mask:0xf
	v_mov_b32_dpp v2, v107 quad_perm:[1,0,3,2] row_mask:0xf bank_mask:0xf
	v_cndmask_b32_e64 v2, v2, v106, s[40:41]
	v_cndmask_b32_e64 v1, v107, v1, s[40:41]
	v_cvt_pk_bf16_f32 v1, v2, v1
	v_add_u32_e32 v2, 0xc800, v0
	global_store_dword v2, v1, s[76:77]
	v_mov_b32_e32 v1, v197
	v_mov_b32_e32 v2, v197
	s_nop 0
	v_mov_b32_dpp v1, v108 quad_perm:[1,0,3,2] row_mask:0xf bank_mask:0xf
	v_mov_b32_dpp v2, v109 quad_perm:[1,0,3,2] row_mask:0xf bank_mask:0xf
	v_cndmask_b32_e64 v2, v2, v108, s[40:41]
	v_cndmask_b32_e64 v1, v109, v1, s[40:41]
	v_cvt_pk_bf16_f32 v1, v2, v1
	v_add_u32_e32 v2, 0xe000, v0
	global_store_dword v2, v1, s[76:77]
	v_mov_b32_e32 v1, v197
	v_mov_b32_e32 v2, v197
	v_add_u32_e32 v0, 0xe800, v0
	v_mov_b32_dpp v1, v110 quad_perm:[1,0,3,2] row_mask:0xf bank_mask:0xf
	v_mov_b32_dpp v2, v111 quad_perm:[1,0,3,2] row_mask:0xf bank_mask:0xf
	v_cndmask_b32_e64 v1, v111, v1, s[40:41]
	v_cndmask_b32_e64 v2, v2, v110, s[40:41]
	v_cvt_pk_bf16_f32 v1, v2, v1
	global_store_dword v0, v1, s[76:77]
	s_waitcnt lgkmcnt(0)
	s_barrier
	s_mov_b64 s[76:77], 0
	s_mov_b64 s[34:35], 0x800
